# xor-16/32 steps of wave sum reductions (st3 rowfin, phase-0 loops, final norm) via permlane16/32 swaps instead of ds_bpermute+wait
# speedup vs baseline: 1.0049x; 1.0019x over previous
.LBB0_17:
	global_load_dwordx4 v[12:15], v[2:3], off offset:-3072
	global_load_dwordx4 v[16:19], v[2:3], off offset:-2048
	global_load_dwordx4 v[20:23], v[2:3], off offset:-1024
	global_load_dwordx4 v[24:27], v[2:3], off
	global_load_dwordx4 v[28:31], v[0:1], off
	v_add_u32_e32 v4, s6, v4
	s_waitcnt vmcnt(4)
	v_mov_b32_e32 v34, v13
	s_waitcnt vmcnt(3)
	v_mov_b32_e32 v35, v17
	v_mov_b32_e32 v32, v12
	v_mov_b32_e32 v33, v16
	s_waitcnt vmcnt(2)
	v_mov_b32_e32 v42, v21
	s_waitcnt vmcnt(1)
	v_mov_b32_e32 v43, v25
	v_pk_mul_f32 v[34:35], v[34:35], v[34:35]
	v_mov_b32_e32 v36, v14
	v_mov_b32_e32 v37, v18
	v_mov_b32_e32 v40, v20
	v_mov_b32_e32 v41, v24
	v_pk_mul_f32 v[42:43], v[42:43], v[42:43]
	v_pk_fma_f32 v[32:33], v[32:33], v[32:33], v[34:35]
	v_mov_b32_e32 v38, v15
	v_mov_b32_e32 v39, v19
	v_mov_b32_e32 v44, v22
	v_mov_b32_e32 v45, v26
	v_pk_fma_f32 v[34:35], v[40:41], v[40:41], v[42:43]
	v_pk_fma_f32 v[32:33], v[36:37], v[36:37], v[32:33]
	v_mov_b32_e32 v46, v23
	v_mov_b32_e32 v47, v27
	v_pk_fma_f32 v[34:35], v[44:45], v[44:45], v[34:35]
	v_pk_fma_f32 v[32:33], v[38:39], v[38:39], v[32:33]
	v_pk_fma_f32 v[34:35], v[46:47], v[46:47], v[34:35]
	v_add_f32_e32 v11, v32, v33
	v_add_f32_e32 v11, v11, v34
	v_add_f32_e32 v11, v11, v35
	s_nop 1
	v_mov_b32_dpp v32, v11 quad_perm:[1,0,3,2] row_mask:0xf bank_mask:0xf
	s_waitcnt lgkmcnt(0)
	v_add_f32_e32 v11, v11, v32
	s_nop 1
	v_mov_b32_dpp v32, v11 quad_perm:[2,3,0,1] row_mask:0xf bank_mask:0xf
	s_waitcnt lgkmcnt(0)
	v_add_f32_e32 v11, v11, v32
	s_nop 1
	v_mov_b32_dpp v32, v11 row_half_mirror row_mask:0xf bank_mask:0xf
	s_waitcnt lgkmcnt(0)
	v_add_f32_e32 v11, v11, v32
	s_nop 1
	v_mov_b32_dpp v32, v11 row_mirror row_mask:0xf bank_mask:0xf
	s_waitcnt lgkmcnt(0)
	v_add_f32_e32 v11, v11, v32
	v_mov_b32_e32 v32, v11
	v_mov_b32_e32 v42, v11
	s_nop 1
	v_permlane16_swap_b32_e32 v32, v42
	s_waitcnt lgkmcnt(0)
	v_add_f32_e32 v11, v32, v42
	v_mov_b32_e32 v32, v11
	v_mov_b32_e32 v42, v11
	s_nop 1
	v_permlane32_swap_b32_e32 v32, v42
	s_waitcnt lgkmcnt(0)
	v_add_f32_e32 v11, v32, v42
	v_fmamk_f32 v11, v11, 0x3a800000, v187
	v_mul_f32_e32 v32, 0x4b800000, v11
	v_cmp_gt_f32_e32 vcc, s28, v11
	s_nop 1
	v_cndmask_b32_e32 v11, v11, v32, vcc
	v_rsq_f32_e32 v11, v11
	s_nop 0
	v_mul_f32_e32 v32, 0x45800000, v11
	v_cndmask_b32_e32 v32, v11, v32, vcc
	v_pk_mul_f32 v[12:13], v[12:13], v[32:33] op_sel_hi:[1,0]
	v_pk_mul_f32 v[14:15], v[14:15], v[32:33] op_sel_hi:[1,0]
	s_waitcnt vmcnt(0)
	v_pk_mul_f32 v[12:13], v[28:29], v[12:13]
	v_pk_mul_f32 v[14:15], v[30:31], v[14:15]
	global_store_dwordx4 v[2:3], v[12:15], off offset:-3072
	global_load_dwordx4 v[12:15], v[0:1], off offset:1024
	v_pk_mul_f32 v[18:19], v[18:19], v[32:33] op_sel_hi:[1,0]
	v_pk_mul_f32 v[16:17], v[16:17], v[32:33] op_sel_hi:[1,0]
	v_cmp_lt_i32_e32 vcc, s61, v4
	s_or_b64 s[10:11], vcc, s[10:11]
	s_waitcnt vmcnt(0)
	v_pk_mul_f32 v[12:13], v[12:13], v[16:17]
	v_pk_mul_f32 v[14:15], v[14:15], v[18:19]
	global_store_dwordx4 v[2:3], v[12:15], off offset:-2048
	global_load_dwordx4 v[12:15], v[0:1], off offset:2048
	v_pk_mul_f32 v[16:17], v[22:23], v[32:33] op_sel_hi:[1,0]
	v_pk_mul_f32 v[18:19], v[20:21], v[32:33] op_sel_hi:[1,0]
	s_waitcnt vmcnt(0)
	v_pk_mul_f32 v[14:15], v[14:15], v[16:17]
	v_pk_mul_f32 v[12:13], v[12:13], v[18:19]
	global_store_dwordx4 v[2:3], v[12:15], off offset:-1024
	global_load_dwordx4 v[12:15], v[0:1], off offset:3072
	v_pk_mul_f32 v[16:17], v[26:27], v[32:33] op_sel_hi:[1,0]
	v_pk_mul_f32 v[18:19], v[24:25], v[32:33] op_sel_hi:[1,0]
	s_waitcnt vmcnt(0)
	v_pk_mul_f32 v[14:15], v[14:15], v[16:17]
	v_pk_mul_f32 v[12:13], v[12:13], v[18:19]
	global_store_dwordx4 v[2:3], v[12:15], off
	v_lshl_add_u64 v[2:3], v[2:3], 0, s[8:9]
	s_andn2_b64 exec, exec, s[10:11]
	s_cbranch_execnz .LBB0_17

.LBB0_806:
	v_mov_b32_e32 v0, v185
	v_mov_b32_e32 v7, v169
	v_and_b32_e32 v1, 63, v0
	v_ashrrev_i32_e32 v0, 4, v0
	v_and_b32_e32 v0, -4, v0
	v_add_u32_e32 v14, s27, v0
	v_lshlrev_b32_e32 v6, 4, v1
	v_ashrrev_i32_e32 v15, 31, v14
	v_lshl_add_u64 v[12:13], s[6:7], 0, v[6:7]
	v_lshlrev_b64 v[2:3], 10, v[14:15]
	v_lshl_add_u64 v[2:3], v[12:13], 0, v[2:3]
	v_cmp_lt_i32_e32 vcc, v194, v193
	v_lshlrev_b32_e32 v168, 3, v1
	v_lshrrev_b32_e32 v0, 7, v14
	v_ashrrev_i32_e32 v1, 7, v14
	s_movk_i32 s0, 0xffc0
	v_bfi_b32 v0, s0, v1, v0
	v_ashrrev_i32_e32 v1, 31, v0
	v_lshlrev_b64 v[0:1], 10, v[0:1]
	v_lshl_add_u64 v[0:1], s[12:13], 0, v[0:1]
	v_lshl_add_u64 v[4:5], v[0:1], 0, v[6:7]
	v_lshlrev_b64 v[0:1], 11, v[14:15]
	v_lshl_add_u64 v[10:11], s[8:9], 0, v[168:169]
	v_lshl_add_u64 v[8:9], s[10:11], 0, v[168:169]
	v_mov_b32_e32 v160, v14
	v_mov_b32_e32 v161, v15
	v_lshlrev_b64 v[162:163], 10, v[160:161]
	v_lshl_add_u64 v[162:163], v[12:13], 0, v[162:163]
	global_load_dwordx4 v[204:207], v[162:163], off
	v_lshlrev_b64 v[164:165], 9, v[160:161]
	v_lshl_add_u64 v[162:163], v[10:11], 0, v[164:165]
	v_lshl_add_u64 v[164:165], v[8:9], 0, v[164:165]
	global_load_dwordx2 v[220:221], v[162:163], off
	global_load_dwordx2 v[228:229], v[164:165], off
	v_mov_b64_e32 v[166:167], s[82:83]
	s_nop 0
	v_mad_i64_i32 v[166:167], s[0:1], v160, s93, v[166:167]
	v_lshl_add_u64 v[166:167], v[166:167], 0, v[168:169]
	v_add_co_u32_e64 v166, s[0:1], s29, v166
	s_nop 1
	v_addc_co_u32_e64 v167, s[0:1], 0, v167, s[0:1]
	global_load_dwordx2 v[236:237], v[166:167], off offset:3072
	v_add_u32_e32 v160, 1, v14
	v_ashrrev_i32_e32 v161, 31, v160
	v_lshlrev_b64 v[162:163], 10, v[160:161]
	v_lshl_add_u64 v[162:163], v[12:13], 0, v[162:163]
	global_load_dwordx4 v[208:211], v[162:163], off
	v_lshlrev_b64 v[164:165], 9, v[160:161]
	v_lshl_add_u64 v[162:163], v[10:11], 0, v[164:165]
	v_lshl_add_u64 v[164:165], v[8:9], 0, v[164:165]
	global_load_dwordx2 v[222:223], v[162:163], off
	global_load_dwordx2 v[230:231], v[164:165], off
	v_mov_b64_e32 v[166:167], s[82:83]
	s_nop 0
	v_mad_i64_i32 v[166:167], s[0:1], v160, s93, v[166:167]
	v_lshl_add_u64 v[166:167], v[166:167], 0, v[168:169]
	v_add_co_u32_e64 v166, s[0:1], s29, v166
	s_nop 1
	v_addc_co_u32_e64 v167, s[0:1], 0, v167, s[0:1]
	global_load_dwordx2 v[238:239], v[166:167], off offset:3072
	v_add_u32_e32 v160, 2, v14
	v_ashrrev_i32_e32 v161, 31, v160
	v_lshlrev_b64 v[162:163], 10, v[160:161]
	v_lshl_add_u64 v[162:163], v[12:13], 0, v[162:163]
	global_load_dwordx4 v[212:215], v[162:163], off
	v_lshlrev_b64 v[164:165], 9, v[160:161]
	v_lshl_add_u64 v[162:163], v[10:11], 0, v[164:165]
	v_lshl_add_u64 v[164:165], v[8:9], 0, v[164:165]
	global_load_dwordx2 v[224:225], v[162:163], off
	global_load_dwordx2 v[232:233], v[164:165], off
	v_mov_b64_e32 v[166:167], s[82:83]
	s_nop 0
	v_mad_i64_i32 v[166:167], s[0:1], v160, s93, v[166:167]
	v_lshl_add_u64 v[166:167], v[166:167], 0, v[168:169]
	v_add_co_u32_e64 v166, s[0:1], s29, v166
	s_nop 1
	v_addc_co_u32_e64 v167, s[0:1], 0, v167, s[0:1]
	global_load_dwordx2 v[240:241], v[166:167], off offset:3072
	v_add_u32_e32 v160, 3, v14
	v_ashrrev_i32_e32 v161, 31, v160
	v_lshlrev_b64 v[162:163], 10, v[160:161]
	v_lshl_add_u64 v[162:163], v[12:13], 0, v[162:163]
	global_load_dwordx4 v[216:219], v[162:163], off
	v_lshlrev_b64 v[164:165], 9, v[160:161]
	v_lshl_add_u64 v[162:163], v[10:11], 0, v[164:165]
	v_lshl_add_u64 v[164:165], v[8:9], 0, v[164:165]
	global_load_dwordx2 v[226:227], v[162:163], off
	global_load_dwordx2 v[234:235], v[164:165], off
	v_mov_b64_e32 v[166:167], s[82:83]
	s_nop 0
	v_mad_i64_i32 v[166:167], s[0:1], v160, s93, v[166:167]
	v_lshl_add_u64 v[166:167], v[166:167], 0, v[168:169]
	v_add_co_u32_e64 v166, s[0:1], s29, v166
	s_nop 1
	v_addc_co_u32_e64 v167, s[0:1], 0, v167, s[0:1]
	global_load_dwordx2 v[242:243], v[166:167], off offset:3072
	global_load_dwordx4 v[248:251], v[4:5], off
	s_waitcnt vmcnt(0)
	v_mov_b32_e32 v16, v204
	v_mov_b32_e32 v17, v205
	v_mov_b32_e32 v18, v206
	v_mov_b32_e32 v19, v207
	v_and_b32_e32 v21, 0xffff0000, v16
	v_lshlrev_b32_e32 v20, 16, v16
	v_mul_f32_e32 v24, v21, v21
	v_lshlrev_b32_e32 v22, 16, v17
	v_fmac_f32_e32 v24, v20, v20
	v_and_b32_e32 v23, 0xffff0000, v17
	v_fmac_f32_e32 v24, v22, v22
	v_and_b32_e32 v2, 0xffff0000, v18
	v_lshlrev_b32_e32 v3, 16, v18
	v_fmac_f32_e32 v24, v23, v23
	v_pk_mul_f32 v[16:17], v[2:3], v[2:3]
	s_nop 0
	v_add_f32_e32 v17, v17, v24
	v_add_f32_e32 v24, v16, v17
	v_and_b32_e32 v16, 0xffff0000, v19
	v_lshlrev_b32_e32 v17, 16, v19
	v_pk_mul_f32 v[18:19], v[16:17], v[16:17]
	s_nop 0
	v_add_f32_e32 v19, v19, v24
	v_add_f32_e32 v18, v18, v19
	v_cndmask_b32_e32 v19, v191, v194, vcc
	v_lshlrev_b32_e32 v28, 2, v19
	s_nop 1
	v_mov_b32_dpp v19, v18 quad_perm:[1,0,3,2] row_mask:0xf bank_mask:0xf
	v_cmp_lt_i32_e32 vcc, v195, v193
	s_waitcnt lgkmcnt(0)
	v_add_f32_e32 v18, v18, v19
	v_cndmask_b32_e32 v19, v191, v195, vcc
	v_lshlrev_b32_e32 v29, 2, v19
	s_nop 1
	v_mov_b32_dpp v19, v18 quad_perm:[2,3,0,1] row_mask:0xf bank_mask:0xf
	v_cmp_lt_i32_e32 vcc, v196, v193
	s_waitcnt lgkmcnt(0)
	v_add_f32_e32 v18, v18, v19
	v_cndmask_b32_e32 v19, v191, v196, vcc
	v_lshlrev_b32_e32 v30, 2, v19
	s_nop 1
	v_mov_b32_dpp v19, v18 row_half_mirror row_mask:0xf bank_mask:0xf
	v_cmp_lt_i32_e32 vcc, v197, v193
	s_waitcnt lgkmcnt(0)
	v_add_f32_e32 v18, v18, v19
	v_cndmask_b32_e32 v19, v191, v197, vcc
	v_lshlrev_b32_e32 v31, 2, v19
	s_nop 1
	v_mov_b32_dpp v19, v18 row_mirror row_mask:0xf bank_mask:0xf
	v_cmp_lt_i32_e32 vcc, v198, v193
	s_waitcnt lgkmcnt(0)
	v_add_f32_e32 v18, v18, v19
	v_cndmask_b32_e32 v19, v191, v198, vcc
	v_lshlrev_b32_e32 v32, 2, v19
	v_mov_b32_e32 v19, v18
	v_mov_b32_e32 v167, v18
	s_nop 1
	v_permlane16_swap_b32_e32 v19, v167
	v_cmp_lt_i32_e32 vcc, v199, v193
	s_waitcnt lgkmcnt(0)
	v_add_f32_e32 v18, v19, v167
	v_cndmask_b32_e32 v19, v191, v199, vcc
	v_lshlrev_b32_e32 v33, 2, v19
	v_mov_b32_e32 v19, v18
	v_mov_b32_e32 v167, v18
	s_nop 1
	v_permlane32_swap_b32_e32 v19, v167
	s_waitcnt lgkmcnt(0)
	v_add_f32_e32 v24, v19, v167
	v_lshl_add_u64 v[18:19], s[4:5], 0, v[0:1]
	v_fmamk_f32 v0, v24, 0x3b000000, v187
	v_cmp_gt_f32_e32 vcc, s28, v0
	v_mul_f32_e32 v1, 0x4b800000, v0
	s_nop 0
	v_cndmask_b32_e32 v0, v0, v1, vcc
	v_rsq_f32_e32 v0, v0
	s_nop 0
	v_mul_f32_e32 v1, 0x45800000, v0
	v_cndmask_b32_e32 v24, v0, v1, vcc
	v_mul_f32_e32 v0, v24, v20
	v_mul_f32_e32 v1, v24, v21
	v_mul_f32_e32 v3, v24, v3
	v_mul_f32_e32 v2, v24, v2
	v_cvt_pk_bf16_f32 v0, v0, v1
	v_mul_f32_e32 v1, v24, v22
	v_mul_f32_e32 v20, v24, v23
	v_cvt_pk_bf16_f32 v2, v3, v2
	v_mul_f32_e32 v3, v24, v17
	v_mul_f32_e32 v16, v24, v16
	v_cvt_pk_bf16_f32 v1, v1, v20
	v_cvt_pk_bf16_f32 v3, v3, v16
	v_lshl_add_u64 v[16:17], v[18:19], 0, v[6:7]
	global_store_dwordx4 v[16:17], v[0:3], off
	v_mov_b64_e32 v[16:17], s[82:83]
	s_nop 0
	v_lshlrev_b64 v[0:1], 9, v[14:15]
	v_lshl_add_u64 v[2:3], v[10:11], 0, v[0:1]
	v_lshl_add_u64 v[0:1], v[8:9], 0, v[0:1]
	v_mov_b32_e32 v24, v220
	v_mov_b32_e32 v25, v221
	v_mov_b32_e32 v22, v228
	v_mov_b32_e32 v23, v229
	v_mad_i64_i32 v[0:1], s[0:1], v14, s93, v[16:17]
	v_lshl_add_u64 v[0:1], v[0:1], 0, v[168:169]
	v_add_co_u32_e32 v0, vcc, s29, v0
	v_lshlrev_b32_e32 v20, 16, v25
	v_addc_co_u32_e32 v1, vcc, 0, v1, vcc
	v_mov_b32_e32 v26, v236
	v_mov_b32_e32 v27, v237
	s_nop 0
	v_mov_b32_e32 v0, v248
	v_mov_b32_e32 v1, v249
	v_mov_b32_e32 v2, v250
	v_mov_b32_e32 v3, v251
	v_lshlrev_b32_e32 v34, 16, v23
	v_and_b32_e32 v35, 0xffff0000, v23
	v_and_b32_e32 v21, 0xffff0000, v25
	v_lshlrev_b32_e32 v36, 16, v27
	v_mul_f32_e32 v15, 0x3d372713, v36
	v_mul_f32_e32 v15, v15, v36
	v_mov_b32_e32 v23, v36
	v_fmac_f32_e32 v23, v15, v23
	v_mul_f32_e32 v15, 0x3f4c422a, v23
	v_add_f32_e32 v15, v15, v15
	v_and_b32_e32 v37, 0xffff0000, v27
	v_mul_f32_e32 v15, 0x3fb8aa3b, v15
	v_exp_f32_e32 v38, v15
	v_mul_f32_e32 v15, 0x3d372713, v37
	v_pk_fma_f32 v[2:3], v[2:3], v[34:35], v[20:21]
	v_mul_f32_e32 v15, v15, v37
	v_mov_b32_e32 v20, v37
	v_fmac_f32_e32 v20, v15, v20
	v_mul_f32_e32 v15, 0x3f4c422a, v20
	v_add_f32_e32 v15, v15, v15
	v_mul_f32_e32 v15, 0x3fb8aa3b, v15
	v_exp_f32_e32 v39, v15
	s_nop 0
	v_pk_add_f32 v[20:21], v[38:39], 1.0 op_sel_hi:[1,0]
	s_nop 0
	v_div_scale_f32 v15, s[0:1], v21, v21, 2.0
	v_rcp_f32_e32 v23, v15
	s_nop 0
	v_fma_f32 v25, -v15, v23, 1.0
	v_fmac_f32_e32 v23, v25, v23
	v_div_scale_f32 v25, vcc, 2.0, v21, 2.0
	v_mul_f32_e32 v27, v25, v23
	v_fma_f32 v34, -v15, v27, v25
	v_fmac_f32_e32 v27, v34, v23
	v_fma_f32 v15, -v15, v27, v25
	v_div_fmas_f32 v15, v15, v23, v27
	v_div_fixup_f32 v21, v15, v21, 2.0
	v_div_scale_f32 v15, s[0:1], v20, v20, 2.0
	v_rcp_f32_e32 v23, v15
	s_nop 0
	v_fma_f32 v25, -v15, v23, 1.0
	v_fmac_f32_e32 v23, v25, v23
	v_div_scale_f32 v25, vcc, 2.0, v20, 2.0
	v_mul_f32_e32 v27, v25, v23
	v_fma_f32 v34, -v15, v27, v25
	v_fmac_f32_e32 v27, v34, v23
	v_fma_f32 v15, -v15, v27, v25
	v_div_fmas_f32 v15, v15, v23, v27
	v_div_fixup_f32 v20, v15, v20, 2.0
	v_pk_add_f32 v[20:21], v[20:21], 1.0 op_sel_hi:[1,0] neg_lo:[1,0] neg_hi:[1,0]
	v_pk_mul_f32 v[34:35], v[36:37], 0.5 op_sel_hi:[1,0]
	v_pk_add_f32 v[20:21], v[20:21], 1.0 op_sel_hi:[1,0]
	v_lshlrev_b32_e32 v36, 16, v22
	v_pk_mul_f32 v[20:21], v[34:35], v[20:21]
	v_lshlrev_b32_e32 v34, 16, v24
	v_and_b32_e32 v35, 0xffff0000, v24
	v_lshlrev_b32_e32 v24, 16, v26
	v_mul_f32_e32 v15, 0x3d372713, v24
	v_and_b32_e32 v37, 0xffff0000, v22
	v_mul_f32_e32 v15, v15, v24
	v_mov_b32_e32 v22, v24
	v_fmac_f32_e32 v22, v15, v22
	v_mul_f32_e32 v15, 0x3f4c422a, v22
	v_add_f32_e32 v15, v15, v15
	v_and_b32_e32 v25, 0xffff0000, v26
	v_mul_f32_e32 v15, 0x3fb8aa3b, v15
	v_exp_f32_e32 v22, v15
	v_mul_f32_e32 v15, 0x3d372713, v25
	v_mul_f32_e32 v15, v15, v25
	v_mov_b32_e32 v23, v25
	v_fmac_f32_e32 v23, v15, v23
	v_mul_f32_e32 v15, 0x3f4c422a, v23
	v_add_f32_e32 v15, v15, v15
	v_mul_f32_e32 v15, 0x3fb8aa3b, v15
	v_exp_f32_e32 v23, v15
	v_pk_fma_f32 v[0:1], v[0:1], v[36:37], v[34:35]
	v_pk_mul_f32 v[24:25], v[24:25], 0.5 op_sel_hi:[1,0]
	v_pk_mul_f32 v[2:3], v[2:3], v[20:21]
	v_pk_add_f32 v[22:23], v[22:23], 1.0 op_sel_hi:[1,0]
	v_pk_mul_f32 v[20:21], v[2:3], v[2:3]
	v_div_scale_f32 v15, s[0:1], v23, v23, 2.0
	v_rcp_f32_e32 v26, v15
	s_nop 0
	v_fma_f32 v27, -v15, v26, 1.0
	v_fmac_f32_e32 v26, v27, v26
	v_div_scale_f32 v27, vcc, 2.0, v23, 2.0
	v_mul_f32_e32 v34, v27, v26
	v_fma_f32 v35, -v15, v34, v27
	v_fmac_f32_e32 v34, v35, v26
	v_fma_f32 v15, -v15, v34, v27
	v_div_fmas_f32 v15, v15, v26, v34
	v_div_fixup_f32 v23, v15, v23, 2.0
	v_div_scale_f32 v15, s[0:1], v22, v22, 2.0
	v_rcp_f32_e32 v26, v15
	s_nop 0
	v_fma_f32 v27, -v15, v26, 1.0
	v_fmac_f32_e32 v26, v27, v26
	v_div_scale_f32 v27, vcc, 2.0, v22, 2.0
	v_mul_f32_e32 v34, v27, v26
	v_fma_f32 v35, -v15, v34, v27
	v_fmac_f32_e32 v34, v35, v26
	v_fma_f32 v15, -v15, v34, v27
	v_div_fmas_f32 v15, v15, v26, v34
	v_div_fixup_f32 v22, v15, v22, 2.0
	v_pk_add_f32 v[22:23], v[22:23], 1.0 op_sel_hi:[1,0] neg_lo:[1,0] neg_hi:[1,0]
	s_nop 0
	v_pk_add_f32 v[22:23], v[22:23], 1.0 op_sel_hi:[1,0]
	s_nop 0
	v_pk_mul_f32 v[22:23], v[24:25], v[22:23]
	s_nop 0
	v_pk_mul_f32 v[0:1], v[0:1], v[22:23]
	s_nop 0
	v_pk_mul_f32 v[22:23], v[0:1], v[0:1]
	s_nop 0
	v_add_f32_e32 v15, v22, v23
	v_add_f32_e32 v15, v20, v15
	v_add_f32_e32 v15, v21, v15
	s_nop 1
	v_mov_b32_dpp v20, v15 quad_perm:[1,0,3,2] row_mask:0xf bank_mask:0xf
	s_waitcnt lgkmcnt(0)
	v_add_f32_e32 v15, v15, v20
	s_nop 1
	v_mov_b32_dpp v20, v15 quad_perm:[2,3,0,1] row_mask:0xf bank_mask:0xf
	s_waitcnt lgkmcnt(0)
	v_add_f32_e32 v15, v15, v20
	s_nop 1
	v_mov_b32_dpp v20, v15 row_half_mirror row_mask:0xf bank_mask:0xf
	s_waitcnt lgkmcnt(0)
	v_add_f32_e32 v15, v15, v20
	s_nop 1
	v_mov_b32_dpp v20, v15 row_mirror row_mask:0xf bank_mask:0xf
	s_waitcnt lgkmcnt(0)
	v_add_f32_e32 v15, v15, v20
	v_mov_b32_e32 v20, v15
	v_mov_b32_e32 v167, v15
	s_nop 1
	v_permlane16_swap_b32_e32 v20, v167
	s_waitcnt lgkmcnt(0)
	v_add_f32_e32 v15, v20, v167
	v_mov_b32_e32 v20, v15
	v_mov_b32_e32 v167, v15
	s_nop 1
	v_permlane32_swap_b32_e32 v20, v167
	s_waitcnt lgkmcnt(0)
	v_add_f32_e32 v15, v20, v167
	v_fmamk_f32 v15, v15, 0x3b800000, v187
	v_cmp_gt_f32_e32 vcc, s28, v15
	v_mul_f32_e32 v20, 0x4b800000, v15
	s_nop 0
	v_cndmask_b32_e32 v15, v15, v20, vcc
	v_rsq_f32_e32 v15, v15
	s_nop 0
	v_mul_f32_e32 v20, 0x45800000, v15
	v_cndmask_b32_e32 v20, v15, v20, vcc
	v_pk_mul_f32 v[0:1], v[0:1], v[20:21] op_sel_hi:[1,0]
	v_pk_mul_f32 v[2:3], v[2:3], v[20:21] op_sel_hi:[1,0]
	v_cvt_pk_bf16_f32 v0, v0, v1
	v_cvt_pk_bf16_f32 v1, v2, v3
	v_lshl_add_u64 v[2:3], v[18:19], 0, v[168:169]
	global_store_dwordx2 v[2:3], v[0:1], off offset:1536
	v_add_u32_e32 v0, 1, v14
	v_ashrrev_i32_e32 v1, 31, v0
	v_lshlrev_b64 v[18:19], 10, v[0:1]
	v_lshl_add_u64 v[18:19], v[12:13], 0, v[18:19]
	v_mov_b32_e32 v18, v208
	v_mov_b32_e32 v19, v209
	v_mov_b32_e32 v20, v210
	v_mov_b32_e32 v21, v211
	v_lshlrev_b64 v[2:3], 11, v[0:1]
	v_and_b32_e32 v26, 0xffff0000, v18
	v_lshlrev_b32_e32 v15, 16, v18
	v_mul_f32_e32 v24, v26, v26
	v_lshlrev_b32_e32 v27, 16, v19
	v_fmac_f32_e32 v24, v15, v15
	v_and_b32_e32 v34, 0xffff0000, v19
	v_fmac_f32_e32 v24, v27, v27
	v_and_b32_e32 v22, 0xffff0000, v20
	v_lshlrev_b32_e32 v23, 16, v20
	v_fmac_f32_e32 v24, v34, v34
	v_pk_mul_f32 v[18:19], v[22:23], v[22:23]
	v_lshlrev_b32_e32 v25, 16, v21
	v_add_f32_e32 v19, v19, v24
	v_and_b32_e32 v24, 0xffff0000, v21
	v_add_f32_e32 v20, v18, v19
	v_pk_mul_f32 v[18:19], v[24:25], v[24:25]
	s_nop 0
	v_add_f32_e32 v19, v19, v20
	v_add_f32_e32 v18, v18, v19
	s_nop 1
	v_mov_b32_dpp v19, v18 quad_perm:[1,0,3,2] row_mask:0xf bank_mask:0xf
	s_waitcnt lgkmcnt(0)
	v_add_f32_e32 v18, v18, v19
	s_nop 1
	v_mov_b32_dpp v19, v18 quad_perm:[2,3,0,1] row_mask:0xf bank_mask:0xf
	s_waitcnt lgkmcnt(0)
	v_add_f32_e32 v18, v18, v19
	s_nop 1
	v_mov_b32_dpp v19, v18 row_half_mirror row_mask:0xf bank_mask:0xf
	s_waitcnt lgkmcnt(0)
	v_add_f32_e32 v18, v18, v19
	s_nop 1
	v_mov_b32_dpp v19, v18 row_mirror row_mask:0xf bank_mask:0xf
	s_waitcnt lgkmcnt(0)
	v_add_f32_e32 v18, v18, v19
	v_mov_b32_e32 v19, v18
	v_mov_b32_e32 v167, v18
	s_nop 1
	v_permlane16_swap_b32_e32 v19, v167
	s_waitcnt lgkmcnt(0)
	v_add_f32_e32 v18, v19, v167
	v_mov_b32_e32 v19, v18
	v_mov_b32_e32 v167, v18
	s_nop 1
	v_permlane32_swap_b32_e32 v19, v167
	s_waitcnt lgkmcnt(0)
	v_add_f32_e32 v20, v19, v167
	v_lshl_add_u64 v[18:19], s[4:5], 0, v[2:3]
	v_fmamk_f32 v2, v20, 0x3b000000, v187
	v_cmp_gt_f32_e32 vcc, s28, v2
	v_mul_f32_e32 v3, 0x4b800000, v2
	s_nop 0
	v_cndmask_b32_e32 v2, v2, v3, vcc
	v_rsq_f32_e32 v2, v2
	s_nop 0
	v_mul_f32_e32 v3, 0x45800000, v2
	v_cndmask_b32_e32 v2, v2, v3, vcc
	v_mul_f32_e32 v3, v2, v15
	v_mul_f32_e32 v15, v2, v26
	v_cvt_pk_bf16_f32 v20, v3, v15
	v_mul_f32_e32 v3, v2, v27
	v_mul_f32_e32 v15, v2, v34
	v_cvt_pk_bf16_f32 v21, v3, v15
	v_mul_f32_e32 v3, v2, v23
	v_mul_f32_e32 v15, v2, v22
	v_cvt_pk_bf16_f32 v22, v3, v15
	v_mul_f32_e32 v3, v2, v25
	v_mul_f32_e32 v2, v2, v24
	v_cvt_pk_bf16_f32 v23, v3, v2
	v_lshl_add_u64 v[2:3], v[18:19], 0, v[6:7]
	global_store_dwordx4 v[2:3], v[20:23], off
	v_lshlrev_b64 v[2:3], 9, v[0:1]
	v_mad_i64_i32 v[0:1], s[0:1], v0, s93, v[16:17]
	v_lshl_add_u64 v[0:1], v[0:1], 0, v[168:169]
	v_add_co_u32_e32 v0, vcc, s29, v0
	v_lshl_add_u64 v[20:21], v[10:11], 0, v[2:3]
	v_lshl_add_u64 v[2:3], v[8:9], 0, v[2:3]
	v_addc_co_u32_e32 v1, vcc, 0, v1, vcc
	v_mov_b32_e32 v24, v222
	v_mov_b32_e32 v25, v223
	v_mov_b32_e32 v22, v230
	v_mov_b32_e32 v23, v231
	v_mov_b32_e32 v26, v238
	v_mov_b32_e32 v27, v239
	s_nop 0
	v_mov_b32_e32 v0, v248
	v_mov_b32_e32 v1, v249
	v_mov_b32_e32 v2, v250
	v_mov_b32_e32 v3, v251
	v_lshlrev_b32_e32 v20, 16, v25
	v_lshlrev_b32_e32 v36, 16, v27
	v_mul_f32_e32 v15, 0x3d372713, v36
	v_lshlrev_b32_e32 v34, 16, v23
	v_and_b32_e32 v35, 0xffff0000, v23
	v_mul_f32_e32 v15, v15, v36
	v_mov_b32_e32 v23, v36
	v_fmac_f32_e32 v23, v15, v23
	v_mul_f32_e32 v15, 0x3f4c422a, v23
	v_add_f32_e32 v15, v15, v15
	v_and_b32_e32 v37, 0xffff0000, v27
	v_mul_f32_e32 v15, 0x3fb8aa3b, v15
	v_and_b32_e32 v21, 0xffff0000, v25
	v_exp_f32_e32 v38, v15
	v_mul_f32_e32 v15, 0x3d372713, v37
	v_pk_fma_f32 v[2:3], v[2:3], v[34:35], v[20:21]
	v_mul_f32_e32 v15, v15, v37
	v_mov_b32_e32 v20, v37
	v_fmac_f32_e32 v20, v15, v20
	v_mul_f32_e32 v15, 0x3f4c422a, v20
	v_add_f32_e32 v15, v15, v15
	v_mul_f32_e32 v15, 0x3fb8aa3b, v15
	v_exp_f32_e32 v39, v15
	s_nop 0
	v_pk_add_f32 v[20:21], v[38:39], 1.0 op_sel_hi:[1,0]
	s_nop 0
	v_div_scale_f32 v15, s[0:1], v21, v21, 2.0
	v_rcp_f32_e32 v23, v15
	s_nop 0
	v_fma_f32 v25, -v15, v23, 1.0
	v_fmac_f32_e32 v23, v25, v23
	v_div_scale_f32 v25, vcc, 2.0, v21, 2.0
	v_mul_f32_e32 v27, v25, v23
	v_fma_f32 v34, -v15, v27, v25
	v_fmac_f32_e32 v27, v34, v23
	v_fma_f32 v15, -v15, v27, v25
	v_div_fmas_f32 v15, v15, v23, v27
	v_div_fixup_f32 v21, v15, v21, 2.0
	v_div_scale_f32 v15, s[0:1], v20, v20, 2.0
	v_rcp_f32_e32 v23, v15
	s_nop 0
	v_fma_f32 v25, -v15, v23, 1.0
	v_fmac_f32_e32 v23, v25, v23
	v_div_scale_f32 v25, vcc, 2.0, v20, 2.0
	v_mul_f32_e32 v27, v25, v23
	v_fma_f32 v34, -v15, v27, v25
	v_fmac_f32_e32 v27, v34, v23
	v_fma_f32 v15, -v15, v27, v25
	v_div_fmas_f32 v15, v15, v23, v27
	v_div_fixup_f32 v20, v15, v20, 2.0
	v_pk_add_f32 v[20:21], v[20:21], 1.0 op_sel_hi:[1,0] neg_lo:[1,0] neg_hi:[1,0]
	v_pk_mul_f32 v[34:35], v[36:37], 0.5 op_sel_hi:[1,0]
	v_pk_add_f32 v[20:21], v[20:21], 1.0 op_sel_hi:[1,0]
	v_lshlrev_b32_e32 v36, 16, v22
	v_pk_mul_f32 v[20:21], v[34:35], v[20:21]
	v_lshlrev_b32_e32 v34, 16, v24
	v_and_b32_e32 v35, 0xffff0000, v24
	v_lshlrev_b32_e32 v24, 16, v26
	v_mul_f32_e32 v15, 0x3d372713, v24
	v_and_b32_e32 v37, 0xffff0000, v22
	v_mul_f32_e32 v15, v15, v24
	v_mov_b32_e32 v22, v24
	v_fmac_f32_e32 v22, v15, v22
	v_mul_f32_e32 v15, 0x3f4c422a, v22
	v_add_f32_e32 v15, v15, v15
	v_and_b32_e32 v25, 0xffff0000, v26
	v_mul_f32_e32 v15, 0x3fb8aa3b, v15
	v_exp_f32_e32 v22, v15
	v_mul_f32_e32 v15, 0x3d372713, v25
	v_mul_f32_e32 v15, v15, v25
	v_mov_b32_e32 v23, v25
	v_fmac_f32_e32 v23, v15, v23
	v_mul_f32_e32 v15, 0x3f4c422a, v23
	v_add_f32_e32 v15, v15, v15
	v_mul_f32_e32 v15, 0x3fb8aa3b, v15
	v_exp_f32_e32 v23, v15
	v_pk_fma_f32 v[0:1], v[0:1], v[36:37], v[34:35]
	v_pk_mul_f32 v[24:25], v[24:25], 0.5 op_sel_hi:[1,0]
	v_pk_mul_f32 v[2:3], v[2:3], v[20:21]
	v_pk_add_f32 v[22:23], v[22:23], 1.0 op_sel_hi:[1,0]
	v_pk_mul_f32 v[20:21], v[2:3], v[2:3]
	v_div_scale_f32 v15, s[0:1], v23, v23, 2.0
	v_rcp_f32_e32 v26, v15
	s_nop 0
	v_fma_f32 v27, -v15, v26, 1.0
	v_fmac_f32_e32 v26, v27, v26
	v_div_scale_f32 v27, vcc, 2.0, v23, 2.0
	v_mul_f32_e32 v34, v27, v26
	v_fma_f32 v35, -v15, v34, v27
	v_fmac_f32_e32 v34, v35, v26
	v_fma_f32 v15, -v15, v34, v27
	v_div_fmas_f32 v15, v15, v26, v34
	v_div_fixup_f32 v23, v15, v23, 2.0
	v_div_scale_f32 v15, s[0:1], v22, v22, 2.0
	v_rcp_f32_e32 v26, v15
	s_nop 0
	v_fma_f32 v27, -v15, v26, 1.0
	v_fmac_f32_e32 v26, v27, v26
	v_div_scale_f32 v27, vcc, 2.0, v22, 2.0
	v_mul_f32_e32 v34, v27, v26
	v_fma_f32 v35, -v15, v34, v27
	v_fmac_f32_e32 v34, v35, v26
	v_fma_f32 v15, -v15, v34, v27
	v_div_fmas_f32 v15, v15, v26, v34
	v_div_fixup_f32 v22, v15, v22, 2.0
	v_pk_add_f32 v[22:23], v[22:23], 1.0 op_sel_hi:[1,0] neg_lo:[1,0] neg_hi:[1,0]
	s_nop 0
	v_pk_add_f32 v[22:23], v[22:23], 1.0 op_sel_hi:[1,0]
	s_nop 0
	v_pk_mul_f32 v[22:23], v[24:25], v[22:23]
	s_nop 0
	v_pk_mul_f32 v[0:1], v[0:1], v[22:23]
	s_nop 0
	v_pk_mul_f32 v[22:23], v[0:1], v[0:1]
	s_nop 0
	v_add_f32_e32 v15, v22, v23
	v_add_f32_e32 v15, v20, v15
	v_add_f32_e32 v15, v21, v15
	s_nop 1
	v_mov_b32_dpp v20, v15 quad_perm:[1,0,3,2] row_mask:0xf bank_mask:0xf
	s_waitcnt lgkmcnt(0)
	v_add_f32_e32 v15, v15, v20
	s_nop 1
	v_mov_b32_dpp v20, v15 quad_perm:[2,3,0,1] row_mask:0xf bank_mask:0xf
	s_waitcnt lgkmcnt(0)
	v_add_f32_e32 v15, v15, v20
	s_nop 1
	v_mov_b32_dpp v20, v15 row_half_mirror row_mask:0xf bank_mask:0xf
	s_waitcnt lgkmcnt(0)
	v_add_f32_e32 v15, v15, v20
	s_nop 1
	v_mov_b32_dpp v20, v15 row_mirror row_mask:0xf bank_mask:0xf
	s_waitcnt lgkmcnt(0)
	v_add_f32_e32 v15, v15, v20
	v_mov_b32_e32 v20, v15
	v_mov_b32_e32 v167, v15
	s_nop 1
	v_permlane16_swap_b32_e32 v20, v167
	s_waitcnt lgkmcnt(0)
	v_add_f32_e32 v15, v20, v167
	v_mov_b32_e32 v20, v15
	v_mov_b32_e32 v167, v15
	s_nop 1
	v_permlane32_swap_b32_e32 v20, v167
	s_waitcnt lgkmcnt(0)
	v_add_f32_e32 v15, v20, v167
	v_fmamk_f32 v15, v15, 0x3b800000, v187
	v_cmp_gt_f32_e32 vcc, s28, v15
	v_mul_f32_e32 v20, 0x4b800000, v15
	s_nop 0
	v_cndmask_b32_e32 v15, v15, v20, vcc
	v_rsq_f32_e32 v15, v15
	s_nop 0
	v_mul_f32_e32 v20, 0x45800000, v15
	v_cndmask_b32_e32 v20, v15, v20, vcc
	v_pk_mul_f32 v[0:1], v[0:1], v[20:21] op_sel_hi:[1,0]
	v_pk_mul_f32 v[2:3], v[2:3], v[20:21] op_sel_hi:[1,0]
	v_cvt_pk_bf16_f32 v0, v0, v1
	v_cvt_pk_bf16_f32 v1, v2, v3
	v_lshl_add_u64 v[2:3], v[18:19], 0, v[168:169]
	global_store_dwordx2 v[2:3], v[0:1], off offset:1536
	v_add_u32_e32 v0, 2, v14
	v_ashrrev_i32_e32 v1, 31, v0
	v_lshlrev_b64 v[18:19], 10, v[0:1]
	v_lshl_add_u64 v[18:19], v[12:13], 0, v[18:19]
	v_mov_b32_e32 v18, v212
	v_mov_b32_e32 v19, v213
	v_mov_b32_e32 v20, v214
	v_mov_b32_e32 v21, v215
	v_lshlrev_b64 v[2:3], 11, v[0:1]
	v_and_b32_e32 v26, 0xffff0000, v18
	v_lshlrev_b32_e32 v15, 16, v18
	v_mul_f32_e32 v24, v26, v26
	v_lshlrev_b32_e32 v27, 16, v19
	v_fmac_f32_e32 v24, v15, v15
	v_and_b32_e32 v34, 0xffff0000, v19
	v_fmac_f32_e32 v24, v27, v27
	v_and_b32_e32 v22, 0xffff0000, v20
	v_lshlrev_b32_e32 v23, 16, v20
	v_fmac_f32_e32 v24, v34, v34
	v_pk_mul_f32 v[18:19], v[22:23], v[22:23]
	v_lshlrev_b32_e32 v25, 16, v21
	v_add_f32_e32 v19, v19, v24
	v_and_b32_e32 v24, 0xffff0000, v21
	v_add_f32_e32 v20, v18, v19
	v_pk_mul_f32 v[18:19], v[24:25], v[24:25]
	s_nop 0
	v_add_f32_e32 v19, v19, v20
	v_add_f32_e32 v18, v18, v19
	s_nop 1
	v_mov_b32_dpp v19, v18 quad_perm:[1,0,3,2] row_mask:0xf bank_mask:0xf
	s_waitcnt lgkmcnt(0)
	v_add_f32_e32 v18, v18, v19
	s_nop 1
	v_mov_b32_dpp v19, v18 quad_perm:[2,3,0,1] row_mask:0xf bank_mask:0xf
	s_waitcnt lgkmcnt(0)
	v_add_f32_e32 v18, v18, v19
	s_nop 1
	v_mov_b32_dpp v19, v18 row_half_mirror row_mask:0xf bank_mask:0xf
	s_waitcnt lgkmcnt(0)
	v_add_f32_e32 v18, v18, v19
	s_nop 1
	v_mov_b32_dpp v19, v18 row_mirror row_mask:0xf bank_mask:0xf
	s_waitcnt lgkmcnt(0)
	v_add_f32_e32 v18, v18, v19
	v_mov_b32_e32 v19, v18
	v_mov_b32_e32 v167, v18
	s_nop 1
	v_permlane16_swap_b32_e32 v19, v167
	s_waitcnt lgkmcnt(0)
	v_add_f32_e32 v18, v19, v167
	v_mov_b32_e32 v19, v18
	v_mov_b32_e32 v167, v18
	s_nop 1
	v_permlane32_swap_b32_e32 v19, v167
	s_waitcnt lgkmcnt(0)
	v_add_f32_e32 v20, v19, v167
	v_lshl_add_u64 v[18:19], s[4:5], 0, v[2:3]
	v_fmamk_f32 v2, v20, 0x3b000000, v187
	v_cmp_gt_f32_e32 vcc, s28, v2
	v_mul_f32_e32 v3, 0x4b800000, v2
	s_nop 0
	v_cndmask_b32_e32 v2, v2, v3, vcc
	v_rsq_f32_e32 v2, v2
	s_nop 0
	v_mul_f32_e32 v3, 0x45800000, v2
	v_cndmask_b32_e32 v2, v2, v3, vcc
	v_mul_f32_e32 v3, v2, v15
	v_mul_f32_e32 v15, v2, v26
	v_cvt_pk_bf16_f32 v20, v3, v15
	v_mul_f32_e32 v3, v2, v27
	v_mul_f32_e32 v15, v2, v34
	v_cvt_pk_bf16_f32 v21, v3, v15
	v_mul_f32_e32 v3, v2, v23
	v_mul_f32_e32 v15, v2, v22
	v_cvt_pk_bf16_f32 v22, v3, v15
	v_mul_f32_e32 v3, v2, v25
	v_mul_f32_e32 v2, v2, v24
	v_cvt_pk_bf16_f32 v23, v3, v2
	v_lshl_add_u64 v[2:3], v[18:19], 0, v[6:7]
	global_store_dwordx4 v[2:3], v[20:23], off
	v_lshlrev_b64 v[2:3], 9, v[0:1]
	v_mad_i64_i32 v[0:1], s[0:1], v0, s93, v[16:17]
	v_lshl_add_u64 v[0:1], v[0:1], 0, v[168:169]
	v_add_co_u32_e32 v0, vcc, s29, v0
	v_lshl_add_u64 v[20:21], v[10:11], 0, v[2:3]
	v_lshl_add_u64 v[2:3], v[8:9], 0, v[2:3]
	v_addc_co_u32_e32 v1, vcc, 0, v1, vcc
	v_mov_b32_e32 v24, v224
	v_mov_b32_e32 v25, v225
	v_mov_b32_e32 v22, v232
	v_mov_b32_e32 v23, v233
	v_mov_b32_e32 v26, v240
	v_mov_b32_e32 v27, v241
	s_nop 0
	v_mov_b32_e32 v0, v248
	v_mov_b32_e32 v1, v249
	v_mov_b32_e32 v2, v250
	v_mov_b32_e32 v3, v251
	v_lshlrev_b32_e32 v20, 16, v25
	v_lshlrev_b32_e32 v36, 16, v27
	v_mul_f32_e32 v15, 0x3d372713, v36
	v_lshlrev_b32_e32 v34, 16, v23
	v_and_b32_e32 v35, 0xffff0000, v23
	v_mul_f32_e32 v15, v15, v36
	v_mov_b32_e32 v23, v36
	v_fmac_f32_e32 v23, v15, v23
	v_mul_f32_e32 v15, 0x3f4c422a, v23
	v_add_f32_e32 v15, v15, v15
	v_and_b32_e32 v37, 0xffff0000, v27
	v_mul_f32_e32 v15, 0x3fb8aa3b, v15
	v_and_b32_e32 v21, 0xffff0000, v25
	v_exp_f32_e32 v38, v15
	v_mul_f32_e32 v15, 0x3d372713, v37
	v_pk_fma_f32 v[2:3], v[2:3], v[34:35], v[20:21]
	v_mul_f32_e32 v15, v15, v37
	v_mov_b32_e32 v20, v37
	v_fmac_f32_e32 v20, v15, v20
	v_mul_f32_e32 v15, 0x3f4c422a, v20
	v_add_f32_e32 v15, v15, v15
	v_mul_f32_e32 v15, 0x3fb8aa3b, v15
	v_exp_f32_e32 v39, v15
	s_nop 0
	v_pk_add_f32 v[20:21], v[38:39], 1.0 op_sel_hi:[1,0]
	s_nop 0
	v_div_scale_f32 v15, s[0:1], v21, v21, 2.0
	v_rcp_f32_e32 v23, v15
	s_nop 0
	v_fma_f32 v25, -v15, v23, 1.0
	v_fmac_f32_e32 v23, v25, v23
	v_div_scale_f32 v25, vcc, 2.0, v21, 2.0
	v_mul_f32_e32 v27, v25, v23
	v_fma_f32 v34, -v15, v27, v25
	v_fmac_f32_e32 v27, v34, v23
	v_fma_f32 v15, -v15, v27, v25
	v_div_fmas_f32 v15, v15, v23, v27
	v_div_fixup_f32 v21, v15, v21, 2.0
	v_div_scale_f32 v15, s[0:1], v20, v20, 2.0
	v_rcp_f32_e32 v23, v15
	s_nop 0
	v_fma_f32 v25, -v15, v23, 1.0
	v_fmac_f32_e32 v23, v25, v23
	v_div_scale_f32 v25, vcc, 2.0, v20, 2.0
	v_mul_f32_e32 v27, v25, v23
	v_fma_f32 v34, -v15, v27, v25
	v_fmac_f32_e32 v27, v34, v23
	v_fma_f32 v15, -v15, v27, v25
	v_div_fmas_f32 v15, v15, v23, v27
	v_div_fixup_f32 v20, v15, v20, 2.0
	v_pk_add_f32 v[20:21], v[20:21], 1.0 op_sel_hi:[1,0] neg_lo:[1,0] neg_hi:[1,0]
	v_pk_mul_f32 v[34:35], v[36:37], 0.5 op_sel_hi:[1,0]
	v_pk_add_f32 v[20:21], v[20:21], 1.0 op_sel_hi:[1,0]
	v_lshlrev_b32_e32 v36, 16, v22
	v_pk_mul_f32 v[20:21], v[34:35], v[20:21]
	v_lshlrev_b32_e32 v34, 16, v24
	v_and_b32_e32 v35, 0xffff0000, v24
	v_lshlrev_b32_e32 v24, 16, v26
	v_mul_f32_e32 v15, 0x3d372713, v24
	v_and_b32_e32 v37, 0xffff0000, v22
	v_mul_f32_e32 v15, v15, v24
	v_mov_b32_e32 v22, v24
	v_fmac_f32_e32 v22, v15, v22
	v_mul_f32_e32 v15, 0x3f4c422a, v22
	v_add_f32_e32 v15, v15, v15
	v_and_b32_e32 v25, 0xffff0000, v26
	v_mul_f32_e32 v15, 0x3fb8aa3b, v15
	v_exp_f32_e32 v22, v15
	v_mul_f32_e32 v15, 0x3d372713, v25
	v_mul_f32_e32 v15, v15, v25
	v_mov_b32_e32 v23, v25
	v_fmac_f32_e32 v23, v15, v23
	v_mul_f32_e32 v15, 0x3f4c422a, v23
	v_add_f32_e32 v15, v15, v15
	v_mul_f32_e32 v15, 0x3fb8aa3b, v15
	v_exp_f32_e32 v23, v15
	v_pk_fma_f32 v[0:1], v[0:1], v[36:37], v[34:35]
	v_pk_mul_f32 v[24:25], v[24:25], 0.5 op_sel_hi:[1,0]
	v_pk_mul_f32 v[2:3], v[2:3], v[20:21]
	v_pk_add_f32 v[22:23], v[22:23], 1.0 op_sel_hi:[1,0]
	v_pk_mul_f32 v[20:21], v[2:3], v[2:3]
	v_div_scale_f32 v15, s[0:1], v23, v23, 2.0
	v_rcp_f32_e32 v26, v15
	s_nop 0
	v_fma_f32 v27, -v15, v26, 1.0
	v_fmac_f32_e32 v26, v27, v26
	v_div_scale_f32 v27, vcc, 2.0, v23, 2.0
	v_mul_f32_e32 v34, v27, v26
	v_fma_f32 v35, -v15, v34, v27
	v_fmac_f32_e32 v34, v35, v26
	v_fma_f32 v15, -v15, v34, v27
	v_div_fmas_f32 v15, v15, v26, v34
	v_div_fixup_f32 v23, v15, v23, 2.0
	v_div_scale_f32 v15, s[0:1], v22, v22, 2.0
	v_rcp_f32_e32 v26, v15
	s_nop 0
	v_fma_f32 v27, -v15, v26, 1.0
	v_fmac_f32_e32 v26, v27, v26
	v_div_scale_f32 v27, vcc, 2.0, v22, 2.0
	v_mul_f32_e32 v34, v27, v26
	v_fma_f32 v35, -v15, v34, v27
	v_fmac_f32_e32 v34, v35, v26
	v_fma_f32 v15, -v15, v34, v27
	v_div_fmas_f32 v15, v15, v26, v34
	v_div_fixup_f32 v22, v15, v22, 2.0
	v_pk_add_f32 v[22:23], v[22:23], 1.0 op_sel_hi:[1,0] neg_lo:[1,0] neg_hi:[1,0]
	s_nop 0
	v_pk_add_f32 v[22:23], v[22:23], 1.0 op_sel_hi:[1,0]
	s_nop 0
	v_pk_mul_f32 v[22:23], v[24:25], v[22:23]
	s_nop 0
	v_pk_mul_f32 v[0:1], v[0:1], v[22:23]
	s_nop 0
	v_pk_mul_f32 v[22:23], v[0:1], v[0:1]
	s_nop 0
	v_add_f32_e32 v15, v22, v23
	v_add_f32_e32 v15, v20, v15
	v_add_f32_e32 v15, v21, v15
	s_nop 1
	v_mov_b32_dpp v20, v15 quad_perm:[1,0,3,2] row_mask:0xf bank_mask:0xf
	s_waitcnt lgkmcnt(0)
	v_add_f32_e32 v15, v15, v20
	s_nop 1
	v_mov_b32_dpp v20, v15 quad_perm:[2,3,0,1] row_mask:0xf bank_mask:0xf
	s_waitcnt lgkmcnt(0)
	v_add_f32_e32 v15, v15, v20
	s_nop 1
	v_mov_b32_dpp v20, v15 row_half_mirror row_mask:0xf bank_mask:0xf
	s_waitcnt lgkmcnt(0)
	v_add_f32_e32 v15, v15, v20
	s_nop 1
	v_mov_b32_dpp v20, v15 row_mirror row_mask:0xf bank_mask:0xf
	s_waitcnt lgkmcnt(0)
	v_add_f32_e32 v15, v15, v20
	v_mov_b32_e32 v20, v15
	v_mov_b32_e32 v167, v15
	s_nop 1
	v_permlane16_swap_b32_e32 v20, v167
	s_waitcnt lgkmcnt(0)
	v_add_f32_e32 v15, v20, v167
	v_mov_b32_e32 v20, v15
	v_mov_b32_e32 v167, v15
	s_nop 1
	v_permlane32_swap_b32_e32 v20, v167
	s_waitcnt lgkmcnt(0)
	v_add_f32_e32 v15, v20, v167
	v_fmamk_f32 v15, v15, 0x3b800000, v187
	v_cmp_gt_f32_e32 vcc, s28, v15
	v_mul_f32_e32 v20, 0x4b800000, v15
	s_nop 0
	v_cndmask_b32_e32 v15, v15, v20, vcc
	v_rsq_f32_e32 v15, v15
	s_nop 0
	v_mul_f32_e32 v20, 0x45800000, v15
	v_cndmask_b32_e32 v20, v15, v20, vcc
	v_pk_mul_f32 v[0:1], v[0:1], v[20:21] op_sel_hi:[1,0]
	v_pk_mul_f32 v[2:3], v[2:3], v[20:21] op_sel_hi:[1,0]
	v_cvt_pk_bf16_f32 v0, v0, v1
	v_cvt_pk_bf16_f32 v1, v2, v3
	v_lshl_add_u64 v[2:3], v[18:19], 0, v[168:169]
	global_store_dwordx2 v[2:3], v[0:1], off offset:1536
	v_add_u32_e32 v0, 3, v14
	v_ashrrev_i32_e32 v1, 31, v0
	v_lshlrev_b64 v[14:15], 10, v[0:1]
	v_lshl_add_u64 v[12:13], v[12:13], 0, v[14:15]
	v_mov_b32_e32 v12, v216
	v_mov_b32_e32 v13, v217
	v_mov_b32_e32 v14, v218
	v_mov_b32_e32 v15, v219
	v_lshlrev_b64 v[2:3], 11, v[0:1]
	v_and_b32_e32 v19, 0xffff0000, v12
	v_lshlrev_b32_e32 v18, 16, v12
	v_mul_f32_e32 v24, v19, v19
	v_lshlrev_b32_e32 v22, 16, v13
	v_fmac_f32_e32 v24, v18, v18
	v_and_b32_e32 v23, 0xffff0000, v13
	v_fmac_f32_e32 v24, v22, v22
	v_and_b32_e32 v20, 0xffff0000, v14
	v_lshlrev_b32_e32 v21, 16, v14
	v_fmac_f32_e32 v24, v23, v23
	v_pk_mul_f32 v[12:13], v[20:21], v[20:21]
	v_and_b32_e32 v14, 0xffff0000, v15
	v_add_f32_e32 v13, v13, v24
	v_lshlrev_b32_e32 v15, 16, v15
	v_add_f32_e32 v24, v12, v13
	v_pk_mul_f32 v[12:13], v[14:15], v[14:15]
	s_nop 0
	v_add_f32_e32 v13, v13, v24
	v_add_f32_e32 v12, v12, v13
	s_nop 1
	v_mov_b32_dpp v13, v12 quad_perm:[1,0,3,2] row_mask:0xf bank_mask:0xf
	s_waitcnt lgkmcnt(0)
	v_add_f32_e32 v12, v12, v13
	s_nop 1
	v_mov_b32_dpp v13, v12 quad_perm:[2,3,0,1] row_mask:0xf bank_mask:0xf
	s_waitcnt lgkmcnt(0)
	v_add_f32_e32 v12, v12, v13
	s_nop 1
	v_mov_b32_dpp v13, v12 row_half_mirror row_mask:0xf bank_mask:0xf
	s_waitcnt lgkmcnt(0)
	v_add_f32_e32 v12, v12, v13
	s_nop 1
	v_mov_b32_dpp v13, v12 row_mirror row_mask:0xf bank_mask:0xf
	s_waitcnt lgkmcnt(0)
	v_add_f32_e32 v12, v12, v13
	v_mov_b32_e32 v13, v12
	v_mov_b32_e32 v167, v12
	s_nop 1
	v_permlane16_swap_b32_e32 v13, v167
	s_waitcnt lgkmcnt(0)
	v_add_f32_e32 v12, v13, v167
	v_mov_b32_e32 v13, v12
	v_mov_b32_e32 v167, v12
	s_nop 1
	v_permlane32_swap_b32_e32 v13, v167
	s_waitcnt lgkmcnt(0)
	v_add_f32_e32 v24, v13, v167
	v_lshl_add_u64 v[12:13], s[4:5], 0, v[2:3]
	v_fmamk_f32 v2, v24, 0x3b000000, v187
	v_cmp_gt_f32_e32 vcc, s28, v2
	v_mul_f32_e32 v3, 0x4b800000, v2
	s_nop 0
	v_cndmask_b32_e32 v2, v2, v3, vcc
	v_rsq_f32_e32 v2, v2
	s_nop 0
	v_mul_f32_e32 v3, 0x45800000, v2
	v_cndmask_b32_e32 v2, v2, v3, vcc
	v_mul_f32_e32 v3, v2, v18
	v_mul_f32_e32 v18, v2, v19
	v_cvt_pk_bf16_f32 v18, v3, v18
	v_mul_f32_e32 v3, v2, v22
	v_mul_f32_e32 v19, v2, v23
	v_cvt_pk_bf16_f32 v19, v3, v19
	v_mul_f32_e32 v3, v2, v21
	v_mul_f32_e32 v20, v2, v20
	v_cvt_pk_bf16_f32 v20, v3, v20
	v_mul_f32_e32 v3, v2, v15
	v_mul_f32_e32 v2, v2, v14
	v_cvt_pk_bf16_f32 v21, v3, v2
	v_lshl_add_u64 v[2:3], v[12:13], 0, v[6:7]
	global_store_dwordx4 v[2:3], v[18:21], off
	v_lshlrev_b64 v[2:3], 9, v[0:1]
	v_mad_i64_i32 v[0:1], s[0:1], v0, s93, v[16:17]
	v_lshl_add_u64 v[0:1], v[0:1], 0, v[168:169]
	v_lshl_add_u64 v[6:7], v[10:11], 0, v[2:3]
	v_lshl_add_u64 v[2:3], v[8:9], 0, v[2:3]
	v_add_co_u32_e32 v0, vcc, s29, v0
	v_mov_b32_e32 v10, v226
	v_mov_b32_e32 v11, v227
	s_nop 0
	v_addc_co_u32_e32 v1, vcc, 0, v1, vcc
	v_mov_b32_e32 v6, v234
	v_mov_b32_e32 v7, v235
	v_mov_b32_e32 v14, v242
	v_mov_b32_e32 v15, v243
	s_nop 0
	v_mov_b32_e32 v0, v248
	v_mov_b32_e32 v1, v249
	v_mov_b32_e32 v2, v250
	v_mov_b32_e32 v3, v251
	v_lshlrev_b32_e32 v4, 16, v11
	v_and_b32_e32 v5, 0xffff0000, v11
	v_lshlrev_b32_e32 v8, 16, v7
	v_and_b32_e32 v9, 0xffff0000, v7
	v_lshlrev_b32_e32 v16, 16, v15
	v_and_b32_e32 v17, 0xffff0000, v15
	v_mul_f32_e32 v7, 0x3d372713, v16
	v_pk_fma_f32 v[2:3], v[2:3], v[8:9], v[4:5]
	v_mul_f32_e32 v4, 0x3d372713, v17
	v_mul_f32_e32 v7, v7, v16
	v_mov_b32_e32 v11, v16
	v_mul_f32_e32 v4, v4, v17
	v_mov_b32_e32 v5, v17
	v_fmac_f32_e32 v11, v7, v11
	v_fmac_f32_e32 v5, v4, v5
	v_mul_f32_e32 v7, 0x3f4c422a, v11
	v_mul_f32_e32 v4, 0x3f4c422a, v5
	v_add_f32_e32 v7, v7, v7
	v_add_f32_e32 v4, v4, v4
	v_mul_f32_e32 v7, 0x3fb8aa3b, v7
	v_mul_f32_e32 v4, 0x3fb8aa3b, v4
	v_exp_f32_e32 v18, v7
	v_exp_f32_e32 v19, v4
	s_nop 0
	v_pk_add_f32 v[4:5], v[18:19], 1.0 op_sel_hi:[1,0]
	s_nop 0
	v_div_scale_f32 v7, s[0:1], v5, v5, 2.0
	v_rcp_f32_e32 v8, v7
	s_nop 0
	v_fma_f32 v9, -v7, v8, 1.0
	v_fmac_f32_e32 v8, v9, v8
	v_div_scale_f32 v9, vcc, 2.0, v5, 2.0
	v_mul_f32_e32 v11, v9, v8
	v_fma_f32 v15, -v7, v11, v9
	v_fmac_f32_e32 v11, v15, v8
	v_fma_f32 v7, -v7, v11, v9
	v_div_fmas_f32 v7, v7, v8, v11
	v_div_fixup_f32 v5, v7, v5, 2.0
	v_div_scale_f32 v7, s[0:1], v4, v4, 2.0
	v_rcp_f32_e32 v8, v7
	s_nop 0
	v_fma_f32 v9, -v7, v8, 1.0
	v_fmac_f32_e32 v8, v9, v8
	v_div_scale_f32 v9, vcc, 2.0, v4, 2.0
	v_mul_f32_e32 v11, v9, v8
	v_fma_f32 v15, -v7, v11, v9
	v_fmac_f32_e32 v11, v15, v8
	v_fma_f32 v7, -v7, v11, v9
	v_div_fmas_f32 v7, v7, v8, v11
	v_div_fixup_f32 v4, v7, v4, 2.0
	v_pk_add_f32 v[4:5], v[4:5], 1.0 op_sel_hi:[1,0] neg_lo:[1,0] neg_hi:[1,0]
	v_pk_mul_f32 v[8:9], v[16:17], 0.5 op_sel_hi:[1,0]
	v_pk_add_f32 v[4:5], v[4:5], 1.0 op_sel_hi:[1,0]
	v_lshlrev_b32_e32 v16, 16, v10
	v_pk_mul_f32 v[4:5], v[8:9], v[4:5]
	v_lshlrev_b32_e32 v8, 16, v14
	v_and_b32_e32 v17, 0xffff0000, v10
	v_lshlrev_b32_e32 v10, 16, v6
	v_and_b32_e32 v11, 0xffff0000, v6
	v_mul_f32_e32 v6, 0x3d372713, v8
	v_mul_f32_e32 v6, v6, v8
	v_mov_b32_e32 v7, v8
	v_and_b32_e32 v9, 0xffff0000, v14
	v_fmac_f32_e32 v7, v6, v7
	v_mul_f32_e32 v6, 0x3f4c422a, v7
	v_mul_f32_e32 v7, 0x3d372713, v9
	v_pk_fma_f32 v[0:1], v[0:1], v[10:11], v[16:17]
	v_mul_f32_e32 v7, v7, v9
	v_mov_b32_e32 v10, v9
	v_fmac_f32_e32 v10, v7, v10
	v_mul_f32_e32 v7, 0x3f4c422a, v10
	v_add_f32_e32 v6, v6, v6
	v_add_f32_e32 v7, v7, v7
	v_mul_f32_e32 v6, 0x3fb8aa3b, v6
	v_mul_f32_e32 v7, 0x3fb8aa3b, v7
	v_exp_f32_e32 v6, v6
	v_exp_f32_e32 v7, v7
	v_pk_mul_f32 v[8:9], v[8:9], 0.5 op_sel_hi:[1,0]
	v_pk_mul_f32 v[2:3], v[2:3], v[4:5]
	v_pk_add_f32 v[6:7], v[6:7], 1.0 op_sel_hi:[1,0]
	s_nop 0
	v_div_scale_f32 v10, s[0:1], v7, v7, 2.0
	v_rcp_f32_e32 v11, v10
	v_pk_mul_f32 v[4:5], v[2:3], v[2:3]
	v_fma_f32 v14, -v10, v11, 1.0
	v_fmac_f32_e32 v11, v14, v11
	v_div_scale_f32 v14, vcc, 2.0, v7, 2.0
	v_mul_f32_e32 v15, v14, v11
	v_fma_f32 v16, -v10, v15, v14
	v_fmac_f32_e32 v15, v16, v11
	v_fma_f32 v10, -v10, v15, v14
	v_div_fmas_f32 v10, v10, v11, v15
	v_div_fixup_f32 v7, v10, v7, 2.0
	v_div_scale_f32 v10, s[0:1], v6, v6, 2.0
	v_rcp_f32_e32 v11, v10
	s_nop 0
	v_fma_f32 v14, -v10, v11, 1.0
	v_fmac_f32_e32 v11, v14, v11
	v_div_scale_f32 v14, vcc, 2.0, v6, 2.0
	v_mul_f32_e32 v15, v14, v11
	v_fma_f32 v16, -v10, v15, v14
	v_fmac_f32_e32 v15, v16, v11
	v_fma_f32 v10, -v10, v15, v14
	v_div_fmas_f32 v10, v10, v11, v15
	v_div_fixup_f32 v6, v10, v6, 2.0
	v_pk_add_f32 v[6:7], v[6:7], 1.0 op_sel_hi:[1,0] neg_lo:[1,0] neg_hi:[1,0]
	s_nop 0
	v_pk_add_f32 v[6:7], v[6:7], 1.0 op_sel_hi:[1,0]
	s_nop 0
	v_pk_mul_f32 v[6:7], v[8:9], v[6:7]
	s_nop 0
	v_pk_mul_f32 v[0:1], v[0:1], v[6:7]
	s_nop 0
	v_pk_mul_f32 v[6:7], v[0:1], v[0:1]
	s_nop 0
	v_add_f32_e32 v6, v6, v7
	v_add_f32_e32 v4, v4, v6
	v_add_f32_e32 v4, v5, v4
	s_nop 1
	v_mov_b32_dpp v5, v4 quad_perm:[1,0,3,2] row_mask:0xf bank_mask:0xf
	s_waitcnt lgkmcnt(0)
	v_add_f32_e32 v4, v4, v5
	s_nop 1
	v_mov_b32_dpp v5, v4 quad_perm:[2,3,0,1] row_mask:0xf bank_mask:0xf
	s_waitcnt lgkmcnt(0)
	v_add_f32_e32 v4, v4, v5
	s_nop 1
	v_mov_b32_dpp v5, v4 row_half_mirror row_mask:0xf bank_mask:0xf
	s_waitcnt lgkmcnt(0)
	v_add_f32_e32 v4, v4, v5
	s_nop 1
	v_mov_b32_dpp v5, v4 row_mirror row_mask:0xf bank_mask:0xf
	s_waitcnt lgkmcnt(0)
	v_add_f32_e32 v4, v4, v5
	v_mov_b32_e32 v5, v4
	v_mov_b32_e32 v167, v4
	s_nop 1
	v_permlane16_swap_b32_e32 v5, v167
	s_waitcnt lgkmcnt(0)
	v_add_f32_e32 v4, v5, v167
	v_mov_b32_e32 v5, v4
	v_mov_b32_e32 v167, v4
	s_nop 1
	v_permlane32_swap_b32_e32 v5, v167
	s_waitcnt lgkmcnt(0)
	v_add_f32_e32 v4, v5, v167
	v_fmamk_f32 v4, v4, 0x3b800000, v187
	v_cmp_gt_f32_e32 vcc, s28, v4
	v_mul_f32_e32 v5, 0x4b800000, v4
	s_nop 0
	v_cndmask_b32_e32 v4, v4, v5, vcc
	v_rsq_f32_e32 v4, v4
	s_nop 0
	v_mul_f32_e32 v5, 0x45800000, v4
	v_cndmask_b32_e32 v4, v4, v5, vcc
	v_pk_mul_f32 v[0:1], v[0:1], v[4:5] op_sel_hi:[1,0]
	v_pk_mul_f32 v[2:3], v[2:3], v[4:5] op_sel_hi:[1,0]
	v_cvt_pk_bf16_f32 v0, v0, v1
	v_cvt_pk_bf16_f32 v1, v2, v3
	v_lshl_add_u64 v[2:3], v[12:13], 0, v[168:169]
	global_store_dwordx2 v[2:3], v[0:1], off offset:1536
	s_cbranch_execnz .LBB0_803

.LBB0_2006:
	global_load_dwordx4 v[18:21], v[8:9], off offset:-2048
	global_load_dwordx4 v[22:25], v[8:9], off offset:-1024
	global_load_dwordx4 v[26:29], v[8:9], off
	global_load_dwordx4 v[30:33], v[8:9], off offset:1024
	s_waitcnt vmcnt(0)
	v_cvt_pk_bf16_f32 v40, v18, v19
	v_cvt_pk_bf16_f32 v41, v20, v21
	global_store_dwordx2 v[6:7], v[40:41], off offset:-1024
	v_mul_f32_e32 v3, v19, v19
	s_waitcnt lgkmcnt(0)
	v_mul_f32_e32 v17, v21, v21
	v_fmac_f32_e32 v3, v18, v18
	v_fmac_f32_e32 v17, v20, v20
	v_add_f32_e32 v3, v3, v17
	v_cvt_pk_bf16_f32 v40, v22, v23
	v_cvt_pk_bf16_f32 v41, v24, v25
	global_store_dwordx2 v[6:7], v[40:41], off offset:-512
	v_mul_f32_e32 v17, v23, v23
	v_mul_f32_e32 v18, v25, v25
	v_fmac_f32_e32 v17, v22, v22
	v_fmac_f32_e32 v18, v24, v24
	v_add_f32_e32 v17, v17, v18
	v_add_f32_e32 v3, v3, v17
	v_cvt_pk_bf16_f32 v40, v26, v27
	v_cvt_pk_bf16_f32 v41, v28, v29
	global_store_dwordx2 v[6:7], v[40:41], off
	v_mul_f32_e32 v17, v27, v27
	v_mul_f32_e32 v18, v29, v29
	v_fmac_f32_e32 v17, v26, v26
	v_fmac_f32_e32 v18, v28, v28
	v_add_f32_e32 v17, v17, v18
	v_add_f32_e32 v3, v3, v17
	v_mul_f32_e32 v17, v31, v31
	v_mul_f32_e32 v18, v33, v33
	v_fmac_f32_e32 v17, v30, v30
	v_fmac_f32_e32 v18, v32, v32
	v_add_f32_e32 v17, v17, v18
	v_add_f32_e32 v3, v3, v17
	s_nop 1
	v_mov_b32_dpp v17, v3 quad_perm:[1,0,3,2] row_mask:0xf bank_mask:0xf
	v_cvt_pk_bf16_f32 v18, v30, v31
	v_cvt_pk_bf16_f32 v19, v32, v33
	global_store_dwordx2 v[6:7], v[18:19], off offset:512
	s_waitcnt lgkmcnt(0)
	v_add_f32_e32 v3, v3, v17
	s_nop 1
	v_mov_b32_dpp v17, v3 quad_perm:[2,3,0,1] row_mask:0xf bank_mask:0xf
	s_waitcnt lgkmcnt(0)
	v_add_f32_e32 v3, v3, v17
	s_nop 1
	v_mov_b32_dpp v17, v3 row_half_mirror row_mask:0xf bank_mask:0xf
	s_waitcnt lgkmcnt(0)
	v_add_f32_e32 v3, v3, v17
	s_nop 1
	v_mov_b32_dpp v17, v3 row_mirror row_mask:0xf bank_mask:0xf
	s_waitcnt lgkmcnt(0)
	v_add_f32_e32 v3, v3, v17
	v_mov_b32_e32 v17, v3
	v_mov_b32_e32 v42, v3
	s_nop 1
	v_permlane16_swap_b32_e32 v17, v42
	s_waitcnt lgkmcnt(0)
	v_add_f32_e32 v3, v17, v42
	v_mov_b32_e32 v17, v3
	v_mov_b32_e32 v42, v3
	s_nop 1
	v_permlane32_swap_b32_e32 v17, v42
	s_and_saveexec_b64 s[8:9], vcc
	s_cbranch_execz .LBB0_2005
	s_waitcnt lgkmcnt(0)
	v_add_f32_e32 v3, v17, v42
	v_cndmask_b32_e64 v3, 0, v3, s[6:7]
	global_store_dword v[4:5], v3, off
	s_branch .LBB0_2005

.LBB0_2011:
	global_load_dwordx4 v[16:19], v[8:9], off offset:-2048
	global_load_dwordx4 v[20:23], v[8:9], off offset:-1024
	global_load_dwordx4 v[24:27], v[8:9], off
	global_load_dwordx4 v[28:31], v[8:9], off offset:1024
	s_waitcnt vmcnt(0)
	v_cvt_pk_bf16_f32 v40, v16, v17
	v_cvt_pk_bf16_f32 v41, v18, v19
	global_store_dwordx2 v[6:7], v[40:41], off offset:-1024
	v_mul_f32_e32 v1, v17, v17
	s_waitcnt lgkmcnt(0)
	v_mul_f32_e32 v3, v19, v19
	v_fmac_f32_e32 v1, v16, v16
	v_fmac_f32_e32 v3, v18, v18
	v_add_f32_e32 v1, v1, v3
	v_cvt_pk_bf16_f32 v40, v20, v21
	v_cvt_pk_bf16_f32 v41, v22, v23
	global_store_dwordx2 v[6:7], v[40:41], off offset:-512
	v_mul_f32_e32 v3, v21, v21
	v_mul_f32_e32 v16, v23, v23
	v_fmac_f32_e32 v3, v20, v20
	v_fmac_f32_e32 v16, v22, v22
	v_add_f32_e32 v3, v3, v16
	v_add_f32_e32 v1, v1, v3
	v_cvt_pk_bf16_f32 v40, v24, v25
	v_cvt_pk_bf16_f32 v41, v26, v27
	global_store_dwordx2 v[6:7], v[40:41], off
	v_mul_f32_e32 v3, v25, v25
	v_mul_f32_e32 v16, v27, v27
	v_fmac_f32_e32 v3, v24, v24
	v_fmac_f32_e32 v16, v26, v26
	v_add_f32_e32 v3, v3, v16
	v_add_f32_e32 v1, v1, v3
	v_mul_f32_e32 v3, v29, v29
	v_mul_f32_e32 v16, v31, v31
	v_fmac_f32_e32 v3, v28, v28
	v_fmac_f32_e32 v16, v30, v30
	v_add_f32_e32 v3, v3, v16
	v_add_f32_e32 v1, v1, v3
	s_nop 1
	v_mov_b32_dpp v3, v1 quad_perm:[1,0,3,2] row_mask:0xf bank_mask:0xf
	v_cvt_pk_bf16_f32 v16, v28, v29
	v_cvt_pk_bf16_f32 v17, v30, v31
	global_store_dwordx2 v[6:7], v[16:17], off offset:512
	s_waitcnt lgkmcnt(0)
	v_add_f32_e32 v1, v1, v3
	s_nop 1
	v_mov_b32_dpp v3, v1 quad_perm:[2,3,0,1] row_mask:0xf bank_mask:0xf
	s_waitcnt lgkmcnt(0)
	v_add_f32_e32 v1, v1, v3
	s_nop 1
	v_mov_b32_dpp v3, v1 row_half_mirror row_mask:0xf bank_mask:0xf
	s_waitcnt lgkmcnt(0)
	v_add_f32_e32 v1, v1, v3
	s_nop 1
	v_mov_b32_dpp v3, v1 row_mirror row_mask:0xf bank_mask:0xf
	s_waitcnt lgkmcnt(0)
	v_add_f32_e32 v1, v1, v3
	v_mov_b32_e32 v3, v1
	v_mov_b32_e32 v42, v1
	s_nop 1
	v_permlane16_swap_b32_e32 v3, v42
	s_waitcnt lgkmcnt(0)
	v_add_f32_e32 v1, v3, v42
	v_mov_b32_e32 v3, v1
	v_mov_b32_e32 v42, v1
	s_nop 1
	v_permlane32_swap_b32_e32 v3, v42
	s_and_saveexec_b64 s[8:9], vcc
	s_cbranch_execz .LBB0_2010
	s_waitcnt lgkmcnt(0)
	v_add_f32_e32 v1, v3, v42
	v_cndmask_b32_e64 v1, 0, v1, s[6:7]
	global_store_dword v[4:5], v1, off
	s_branch .LBB0_2010
